# SSD scan: all tile2 score blocks (incl. the masked diagonal block, branch-free form) produced once per n-half group in LDS
# baseline (speedup 1.0000x reference)
.LBB0_1648:
	s_or_b64 exec, exec, s[0:1]
	v_readlane_b32 s0, v251, 37
	v_readlane_b32 s1, v251, 38
	s_add_u32 s0, s31, s0
	s_addc_u32 s1, s30, s1
	v_readlane_b32 s4, v253, 16
	s_add_u32 s0, s0, s4
	s_addc_u32 s1, s1, 0
	s_lshl_b32 s4, s9, 1
	v_lshlrev_b32_e32 v115, 2, v3
	s_add_u32 s0, s0, s4
	v_lshlrev_b32_e32 v126, 7, v4
	s_addc_u32 s1, s1, 0
	v_lshlrev_b32_e32 v4, 1, v115
	v_mov_b32_e32 v5, v11
	v_readlane_b32 s4, v250, 8
	v_lshl_add_u64 v[4:5], s[0:1], 0, v[4:5]
	s_mov_b64 s[0:1], 0x48df8000
	s_ashr_i32 s45, s80, 8
	s_lshl_b32 s35, s4, 11
	v_readlane_b32 s5, v253, 63
	v_lshl_add_u64 v[92:93], v[4:5], 0, s[0:1]
	s_lshl_b32 s23, s45, 7
	s_and_b32 s0, s8, 0xfffffc0
	s_add_i32 s1, s5, s35
	s_cmp_gt_i32 s4, 16
	s_cselect_b64 s[82:83], -1, 0
	s_cmp_gt_u32 s4, 33
	s_cselect_b64 s[88:89], -1, 0
	s_lshl_b32 s33, s4, 10
	s_ashr_i32 s81, s33, 31
	s_cmp_gt_i32 s4, 8
	s_cselect_b64 s[90:91], -1, 0
	s_cmp_gt_u32 s12, 33
	s_cselect_b64 s[10:11], -1, 0
	s_lshl_b32 s25, s12, 10
	s_ashr_i32 s93, s25, 31
	v_writelane_b32 v255, s10, 15
	s_cmp_gt_i32 s4, 0
	v_or_b32_e32 v3, s0, v2
	v_writelane_b32 v255, s11, 16
	s_cselect_b64 s[10:11], -1, 0
	v_writelane_b32 v254, s10, 61
	s_cmp_gt_u32 s2, 33
	v_add_u32_e32 v176, s1, v90
	v_writelane_b32 v254, s11, 62
	s_cselect_b64 s[10:11], -1, 0
	s_lshl_b32 s70, s2, 10
	s_ashr_i32 s2, s70, 31
	v_writelane_b32 v255, s10, 19
	s_cmp_gt_i32 s4, -8
	v_add_u32_e32 v127, s5, v90
	v_writelane_b32 v255, s11, 20
	s_cselect_b64 s[10:11], -1, 0
	v_writelane_b32 v254, s10, 59
	s_cmp_gt_u32 s13, 33
	v_writelane_b32 v255, s2, 22
	v_writelane_b32 v254, s11, 60
	s_cselect_b64 s[10:11], -1, 0
	s_lshl_b32 s96, s13, 10
	s_ashr_i32 s2, s96, 31
	v_writelane_b32 v255, s10, 25
	s_cmp_gt_i32 s4, -16
	v_mul_lo_u32 v174, v3, s71
	v_writelane_b32 v255, s11, 26
	s_cselect_b64 s[10:11], -1, 0
	v_writelane_b32 v255, s2, 28
	v_writelane_b32 v254, s10, 63
	s_cmp_gt_u32 s14, 33
	v_or3_b32 v3, v2, s8, 48
	v_writelane_b32 v255, s11, 0
	s_cselect_b64 s[10:11], -1, 0
	s_lshl_b32 s97, s14, 10
	s_ashr_i32 s2, s97, 31
	v_writelane_b32 v255, s10, 31
	s_cmpk_gt_i32 s4, 0xffe8
	v_mul_u32_u24_e32 v128, 0x110, v2
	v_writelane_b32 v255, s11, 32
	s_cselect_b64 s[10:11], -1, 0
	v_writelane_b32 v254, s10, 57
	s_cmp_gt_u32 s15, 33
	v_writelane_b32 v255, s2, 34
	v_writelane_b32 v254, s11, 58
	s_cselect_b64 s[10:11], -1, 0
	s_lshl_b32 s12, s15, 10
	s_ashr_i32 s2, s12, 31
	v_writelane_b32 v255, s10, 42
	s_cmpk_gt_i32 s4, 0xffe0
	s_waitcnt vmcnt(0)
	v_mul_lo_u32 v175, v3, s71
	v_writelane_b32 v255, s11, 43
	s_cselect_b64 s[10:11], -1, 0
	v_writelane_b32 v254, s10, 34
	s_cmp_gt_u32 s16, 33
	v_writelane_b32 v255, s2, 14
	v_writelane_b32 v254, s11, 35
	s_cselect_b64 s[10:11], -1, 0
	s_lshl_b32 s13, s16, 10
	s_ashr_i32 s2, s13, 31
	v_writelane_b32 v255, s10, 17
	s_cmpk_gt_i32 s4, 0xffd8
	v_mov_b32_e32 v3, v11
	v_writelane_b32 v255, s11, 18
	s_cselect_b64 s[10:11], -1, 0
	v_writelane_b32 v254, s10, 40
	s_cmp_gt_u32 s3, 33
	v_writelane_b32 v255, s2, 21
	v_writelane_b32 v254, s11, 41
	s_cselect_b64 s[10:11], -1, 0
	s_lshl_b32 s28, s3, 10
	v_writelane_b32 v255, s10, 23
	s_ashr_i32 s2, s28, 31
	s_cmpk_gt_i32 s4, 0xffd0
	v_writelane_b32 v255, s11, 24
	v_writelane_b32 v255, s2, 27
	s_cselect_b64 s[2:3], -1, 0
	v_writelane_b32 v254, s2, 42
	s_cmp_gt_u32 s6, 33
	v_lshlrev_b32_e32 v4, 1, v126
	v_writelane_b32 v254, s3, 43
	s_cselect_b64 s[2:3], -1, 0
	v_writelane_b32 v255, s2, 29
	s_lshl_b32 s29, s6, 10
	v_mov_b32_e32 v5, v11
	v_writelane_b32 v255, s3, 30
	s_ashr_i32 s2, s29, 31
	s_cmp_gt_u32 s4, 3
	s_cselect_b64 s[40:41], -1, 0
	s_and_b64 s[0:1], s[40:41], exec
	s_cselect_b32 s0, 4, 0
	s_cselect_b32 s1, 16, 0
	v_readlane_b32 s3, v251, 46
	v_or_b32_e32 v177, s1, v2
	s_cselect_b32 s1, 2, 3
	s_or_b32 s0, s0, s3
	s_lshr_b32 s0, 0x65217430, s0
	v_writelane_b32 v255, s2, 33
	s_and_b32 s2, s0, 3
	s_lshl_b32 s18, s2, 4
	s_xor_b32 s0, s35, 0x2000
	s_cmp_gt_u32 s2, 1
	v_add_u32_e32 v178, s0, v127
	s_cselect_b64 s[10:11], -1, 0
	s_lshl_b32 s0, s1, 2
	s_or_b32 s0, s0, s3
	s_lshr_b32 s0, 0x65217430, s0
	s_and_b32 s3, s0, 7
	s_lshl_b32 s19, s3, 4
	s_cmp_gt_u32 s3, 5
	v_lshl_or_b32 v179, s1, 4, v2
	s_cselect_b64 s[16:17], -1, 0
	s_add_i32 s1, 0, 0x22000
	s_add_i32 s8, s33, 0
	s_add_i32 s9, s25, 0
	s_add_i32 s84, s70, 0
	s_add_i32 s85, s96, 0
	s_add_i32 s68, s97, 0
	s_add_i32 s69, s12, 0
	s_add_i32 s14, s13, 0
	s_add_i32 s15, s28, 0
	s_add_i32 s0, s29, 0
	v_lshl_add_u32 v180, v150, 2, s1
	s_lshl_b32 s1, s3, 16
	s_lshl_b32 s4, s2, 16
	v_readlane_b32 s2, v252, 51
	s_add_u32 s2, s31, s2
	v_readlane_b32 s3, v252, 52
	s_addc_u32 s3, s30, s3
	s_add_u32 s5, s2, s33
	v_writelane_b32 v255, s5, 7
	s_addc_u32 s5, s3, 0
	v_writelane_b32 v255, s5, 8
	s_add_u32 s5, s2, s25
	v_writelane_b32 v255, s5, 9
	s_addc_u32 s5, s3, 0
	v_writelane_b32 v255, s5, 10
	s_add_u32 s5, s2, s70
	v_writelane_b32 v255, s5, 11
	s_addc_u32 s5, s3, 0
	v_writelane_b32 v255, s5, 12
	s_add_u32 s5, s2, s96
	v_writelane_b32 v255, s5, 1
	s_addc_u32 s5, s3, 0
	v_writelane_b32 v255, s5, 2
	s_add_u32 s5, s2, s97
	v_writelane_b32 v255, s5, 3
	s_addc_u32 s5, s3, 0
	v_writelane_b32 v255, s5, 4
	s_add_u32 s5, s2, s12
	v_writelane_b32 v255, s5, 5
	s_addc_u32 s5, s3, 0
	v_writelane_b32 v255, s5, 6
	s_add_u32 s5, s2, s13
	v_writelane_b32 v255, s5, 35
	s_addc_u32 s5, s3, 0
	v_writelane_b32 v255, s5, 36
	s_add_u32 s5, s2, s28
	v_writelane_b32 v255, s5, 37
	s_addc_u32 s5, s3, 0
	v_writelane_b32 v255, s5, 38
	s_add_u32 s2, s2, s29
	v_writelane_b32 v255, s2, 39
	s_addc_u32 s2, s3, 0
	v_writelane_b32 v255, s2, 40
	v_readlane_b32 s2, v252, 54
	v_and_b32_e32 v2, 48, v150
	s_add_u32 s2, s31, s2
	v_readlane_b32 s3, v252, 55
	v_lshrrev_b32_e32 v2, 1, v2
	s_addc_u32 s3, s30, s3
	v_lshl_add_u64 v[2:3], v[2:3], 0, v[4:5]
	v_mov_b32_e32 v28, 0
	s_mov_b32 s76, 0
	v_or_b32_e32 v129, 1, v115
	v_or_b32_e32 v130, 2, v115
	v_or_b32_e32 v131, 3, v115
	v_or_b32_e32 v132, 16, v115
	v_or_b32_e32 v133, 17, v115
	v_or_b32_e32 v134, 18, v115
	v_or_b32_e32 v135, 19, v115
	v_or_b32_e32 v136, 32, v115
	v_or_b32_e32 v137, 33, v115
	v_or_b32_e32 v138, 34, v115
	v_or_b32_e32 v139, 35, v115
	v_or_b32_e32 v140, 48, v115
	v_or_b32_e32 v141, 49, v115
	v_or_b32_e32 v142, 50, v115
	v_or_b32_e32 v143, 51, v115
	v_or_b32_e32 v144, 64, v115
	v_or_b32_e32 v145, 0x41, v115
	v_or_b32_e32 v146, 0x42, v115
	v_or_b32_e32 v147, 0x43, v115
	v_or_b32_e32 v148, 0x50, v115
	v_or_b32_e32 v149, 0x51, v115
	v_or_b32_e32 v151, 0x52, v115
	v_or_b32_e32 v161, 0x53, v115
	v_or_b32_e32 v166, 0x60, v115
	v_or_b32_e32 v167, 0x61, v115
	v_or_b32_e32 v168, 0x62, v115
	v_or_b32_e32 v169, 0x63, v115
	v_or_b32_e32 v170, 0x70, v115
	v_or_b32_e32 v171, 0x71, v115
	v_or_b32_e32 v172, 0x72, v115
	v_or_b32_e32 v173, 0x73, v115
	v_add_u32_e32 v94, 0x80, v150
	v_lshl_add_u64 v[96:97], s[2:3], 0, v[2:3]
	s_mov_b64 s[94:95], 0
	v_mov_b32_e32 v29, v28
	v_mov_b32_e32 v30, v28
	v_mov_b32_e32 v31, v28
	v_mov_b32_e32 v32, v28
	v_mov_b32_e32 v33, v28
	v_mov_b32_e32 v34, v28
	v_mov_b32_e32 v35, v28
	v_mov_b32_e32 v36, v28
	v_mov_b32_e32 v37, v28
	v_mov_b32_e32 v38, v28
	v_mov_b32_e32 v39, v28
	v_mov_b32_e32 v40, v28
	v_mov_b32_e32 v41, v28
	v_mov_b32_e32 v42, v28
	v_mov_b32_e32 v43, v28
	s_waitcnt vmcnt(0) lgkmcnt(0)
	s_barrier
	v_readlane_b32 s62, v250, 8
	s_and_b32 s62, s62, 3
	s_cmp_lt_u32 s62, 2
	s_cselect_b32 s56, 1, 0
	s_and_b32 s57, s16, 1
	s_or_b32 s56, s56, s57
	s_lshr_b32 s63, s62, 1
	s_and_b32 s62, s62, 1
	s_lshl_b32 s53, s63, 6
	s_lshl_b32 s54, s62, 5
	s_add_i32 s53, s53, s54
	s_lshl_b32 s54, s53, 1
	s_lshr_b32 s55, s54, 2
	s_add_i32 s55, s55, 64
	s_branch .LBB0_1650
	s_nop 0
	s_nop 0
	s_nop 0
	s_nop 0
	s_nop 0
	s_nop 0
	s_nop 0
	s_nop 0
	s_nop 0
	s_nop 0
	s_nop 0
	s_nop 0
	s_nop 0
	s_nop 0
	s_nop 0
	s_nop 0
	s_nop 0
	s_nop 0
	s_nop 0
	s_nop 0
	s_nop 0
	s_nop 0
	s_nop 0
	s_nop 0

.LBB0_1744:
	s_and_saveexec_b64 s[50:51], s[38:39]
	s_lshl_b32 s52, s5, 10
	v_add_u32_e32 v188, s52, v180
	s_add_i32 s52, s52, 0x221fc
	v_mov_b32_e32 v189, s52
	ds_read_b32 v190, v188
	ds_read_b32 v191, v189
	s_waitcnt lgkmcnt(0)
	v_sub_f32_e32 v190, v191, v190
	v_exp_f32_e32 v190, v190
	v_add_u32_e32 v188, 0x4800, v180
	s_nop 0
	ds_write_b32 v188, v190
	s_or_b64 exec, exec, s[50:51]
	s_mul_i32 s2, s5, 0x11000
	s_add_i32 s2, s2, 0
	s_add_i32 s3, s23, s2
	v_add3_u32 v10, s3, v128, v88
	v_add_u32_e32 v44, 0x4000, v10
	v_cvt_pk_bf16_f32 v2, v28, v29
	v_cvt_pk_bf16_f32 v3, v30, v31
	v_cvt_pk_bf16_f32 v4, v32, v33
	v_cvt_pk_bf16_f32 v5, v34, v35
	ds_read2_b64 v[6:9], v44 offset0:128 offset1:132
	v_cvt_pk_bf16_f32 v48, v36, v37
	v_cvt_pk_bf16_f32 v49, v38, v39
	v_cvt_pk_bf16_f32 v50, v40, v41
	v_cvt_pk_bf16_f32 v51, v42, v43
	ds_read2_b64 v[44:47], v44 offset0:136 offset1:140
	s_waitcnt lgkmcnt(0)
	v_mfma_f32_16x16x32_bf16 v[6:9], v[2:5], v[6:9], 0
	s_lshl_b32 s5, s5, 10
	s_add_i32 s65, s5, 0
	s_add_i32 s65, s65, 0x22000
	v_mfma_f32_16x16x32_bf16 v[52:55], v[48:51], v[44:47], v[6:9]
	v_add_u32_e32 v44, 0x5000, v10
	v_add_u32_e32 v114, s2, v88
	v_lshl_add_u32 v182, v115, 2, s65
	v_mul_u32_u24_e32 v188, 0x110, v179
	v_add3_u32 v188, v188, v114, s53
	v_and_b32_e32 v194, 15, v179
	v_or_b32_e32 v194, s19, v194
	v_lshl_add_u32 v189, v194, 2, s65
	v_add_u32_e32 v193, s54, v182
	ds_read_b64 v[200:201], v188
	ds_read_b32 v192, v189
	ds_read_b128 v[202:205], v193
	s_waitcnt lgkmcnt(0)
	v_sub_f32_e32 v202, v192, v202
	v_sub_f32_e32 v203, v192, v203
	v_sub_f32_e32 v204, v192, v204
	v_sub_f32_e32 v205, v192, v205
	v_exp_f32_e32 v202, v202
	v_exp_f32_e32 v203, v203
	v_exp_f32_e32 v204, v204
	v_exp_f32_e32 v205, v205
	v_lshlrev_b32_e32 v190, 16, v200
	v_and_b32_e32 v191, 0xffff0000, v200
	v_pk_mul_f32 v[202:203], v[202:203], v[190:191]
	v_lshlrev_b32_e32 v190, 16, v201
	v_and_b32_e32 v191, 0xffff0000, v201
	v_pk_mul_f32 v[204:205], v[204:205], v[190:191]
	s_nop 0
	v_cvt_pk_bf16_f32 v200, v202, v203
	v_cvt_pk_bf16_f32 v201, v204, v205
	s_nop 0
	ds_write_b64 v188, v[200:201]
	s_cmp_eq_u32 s56, 0
	s_cbranch_scc1 .Lp2_skip
	ds_read_b64 v[200:201], v188 offset:128
	ds_read_b128 v[202:205], v193 offset:256
	ds_read_b32 v190, v189 offset:512
	v_add_u32_e32 v195, s55, v115
	v_sub_u32_e32 v195, v194, v195
	s_waitcnt lgkmcnt(0)
	v_max_f32_e32 v190, v190, v190
	v_max_f32_e32 v190, 0xda24260, v190
	v_rcp_f32_e32 v190, v190
	v_sub_f32_e32 v202, v192, v202
	v_sub_f32_e32 v203, v192, v203
	v_sub_f32_e32 v204, v192, v204
	v_sub_f32_e32 v205, v192, v205
	v_mul_f32_e32 v190, v1, v190
	v_min_f32_e32 v202, 0, v202
	v_min_f32_e32 v203, 0, v203
	v_min_f32_e32 v204, 0, v204
	v_min_f32_e32 v205, 0, v205
	v_exp_f32_e32 v202, v202
	v_exp_f32_e32 v203, v203
	v_exp_f32_e32 v204, v204
	v_exp_f32_e32 v205, v205
	v_lshlrev_b32_e32 v220, 16, v200
	v_and_b32_e32 v221, 0xffff0000, v200
	v_lshlrev_b32_e32 v248, 16, v201
	v_and_b32_e32 v249, 0xffff0000, v201
	v_mul_f32_e32 v202, v202, v220
	v_mul_f32_e32 v203, v203, v221
	v_mul_f32_e32 v204, v204, v248
	v_mul_f32_e32 v205, v205, v249
	v_add_f32_e32 v220, v190, v220
	v_add_f32_e32 v221, v190, v221
	v_add_f32_e32 v248, v190, v248
	v_add_f32_e32 v249, v190, v249
	v_cmp_eq_u32_e32 vcc, 0, v195
	s_nop 1
	v_cndmask_b32_e32 v220, 0, v220, vcc
	v_cmp_eq_u32_e32 vcc, 1, v195
	s_nop 1
	v_cndmask_b32_e32 v221, 0, v221, vcc
	v_cmp_eq_u32_e32 vcc, 2, v195
	s_nop 1
	v_cndmask_b32_e32 v248, 0, v248, vcc
	v_cmp_eq_u32_e32 vcc, 3, v195
	s_nop 1
	v_cndmask_b32_e32 v249, 0, v249, vcc
	v_cmp_lt_i32_e32 vcc, 0, v195
	s_nop 1
	v_cndmask_b32_e32 v202, v220, v202, vcc
	v_cmp_lt_i32_e32 vcc, 1, v195
	s_nop 1
	v_cndmask_b32_e32 v203, v221, v203, vcc
	v_cmp_lt_i32_e32 vcc, 2, v195
	s_nop 1
	v_cndmask_b32_e32 v204, v248, v204, vcc
	v_cmp_lt_i32_e32 vcc, 3, v195
	s_nop 1
	v_cndmask_b32_e32 v205, v249, v205, vcc
	v_cvt_pk_bf16_f32 v200, v202, v203
	v_cvt_pk_bf16_f32 v201, v204, v205
	s_nop 0
	ds_write_b64 v188, v[200:201] offset:128
.Lp2_skip:
	s_nop 0
	ds_read2_b64 v[6:9], v44 offset0:160 offset1:164
	ds_read2_b64 v[44:47], v44 offset0:168 offset1:172
	s_waitcnt lgkmcnt(0)
	v_mfma_f32_16x16x32_bf16 v[6:9], v[2:5], v[6:9], 0
	s_mov_b64 s[42:43], -1
	s_andn2_b64 vcc, exec, s[10:11]
	v_mfma_f32_16x16x32_bf16 v[56:59], v[48:51], v[44:47], v[6:9]
	v_add_u32_e32 v44, 0x6000, v10
	v_add_u32_e32 v10, 0x7000, v10
	ds_read2_b64 v[60:63], v10 offset0:224 offset1:228
	s_nop 1
	ds_read2_b64 v[6:9], v44 offset0:192 offset1:196
	ds_read2_b64 v[44:47], v44 offset0:200 offset1:204
	s_waitcnt lgkmcnt(0)
	v_mfma_f32_16x16x32_bf16 v[6:9], v[2:5], v[6:9], 0
	v_mfma_f32_16x16x32_bf16 v[44:47], v[48:51], v[44:47], v[6:9]
	s_nop 6
	ds_read2_b64 v[6:9], v10 offset0:232 offset1:236
	v_mfma_f32_16x16x32_bf16 v[2:5], v[2:5], v[60:63], 0
	v_mov_b32_e32 v10, s65
	ds_read_b32 v181, v10 offset:508
	s_waitcnt lgkmcnt(0)
	v_mfma_f32_16x16x32_bf16 v[48:51], v[48:51], v[6:9], v[2:5]
	v_add_u32_e32 v6, s35, v127
	s_nop 2
	v_cndmask_b32_e64 v5, v59, v55, s[40:41]
	v_cndmask_b32_e64 v4, v58, v54, s[40:41]
	v_cndmask_b32_e64 v3, v57, v53, s[40:41]
	v_cndmask_b32_e64 v2, v56, v52, s[40:41]
	ds_write_b128 v6, v[2:5]
	v_cndmask_b32_e64 v5, v47, v51, s[40:41]
	v_cndmask_b32_e64 v4, v46, v50, s[40:41]
	v_cndmask_b32_e64 v3, v45, v49, s[40:41]
	v_cndmask_b32_e64 v2, v44, v48, s[40:41]
	ds_write_b128 v176, v[2:5] offset:1024
	v_mov_b32_e32 v2, v177
	s_waitcnt lgkmcnt(0)
	s_barrier
	s_nop 0
	v_and_b32_e32 v10, 15, v2
	v_or_b32_e32 v86, s18, v10
	v_lshl_add_u32 v3, v86, 2, s65
	v_mad_u64_u32 v[6:7], s[2:3], v2, s71, v[114:115]
	ds_read2st64_b32 v[76:77], v3 offset1:2
	ds_read2_b64 v[2:5], v6 offset1:4
	ds_read2_b64 v[64:67], v6 offset0:8 offset1:12
	ds_read_b128 v[60:63], v178
	ds_read_b128 v[72:75], v182
	ds_read_b128 v[68:71], v182 offset:64
	s_waitcnt lgkmcnt(0)
	v_lshlrev_b32_e32 v84, 16, v2
	v_and_b32_e32 v85, 0xffff0000, v2
	v_lshlrev_b32_e32 v82, 16, v3
	v_and_b32_e32 v83, 0xffff0000, v3
	v_lshlrev_b32_e32 v80, 16, v4
	v_and_b32_e32 v81, 0xffff0000, v4
	v_lshlrev_b32_e32 v78, 16, v5
	v_and_b32_e32 v79, 0xffff0000, v5
	s_cbranch_vccnz .LBB0_1746
	v_sub_f32_e32 v2, v76, v72
	v_sub_f32_e32 v3, v76, v73
	v_sub_f32_e32 v4, v76, v74
	v_sub_f32_e32 v5, v76, v75
	v_sub_f32_e32 v6, v76, v68
	v_sub_f32_e32 v7, v76, v69
	v_sub_f32_e32 v8, v76, v70
	v_sub_f32_e32 v9, v76, v71
	v_exp_f32_e32 v2, v2
	v_exp_f32_e32 v3, v3
	v_exp_f32_e32 v4, v4
	v_exp_f32_e32 v5, v5
	v_exp_f32_e32 v6, v6
	v_exp_f32_e32 v8, v8
	v_exp_f32_e32 v9, v9
	v_exp_f32_e32 v7, v7
	v_pk_mul_f32 v[2:3], v[2:3], v[84:85]
	v_pk_mul_f32 v[4:5], v[4:5], v[82:83]
	v_pk_mul_f32 v[8:9], v[8:9], v[78:79]
	v_pk_mul_f32 v[6:7], v[6:7], v[80:81]
	s_mov_b64 s[42:43], 0

.LBB0_1816:
	s_nop 1
	v_cndmask_b32_e64 v2, v54, v58, s[40:41]
	v_exp_f32_e32 v54, v76
	v_cndmask_b32_e64 v3, v55, v59, s[40:41]
	v_cndmask_b32_e64 v5, v53, v57, s[40:41]
	v_cndmask_b32_e64 v4, v52, v56, s[40:41]
	v_pk_add_f32 v[4:5], v[4:5], v[60:61]
	v_pk_add_f32 v[2:3], v[2:3], v[62:63]
	v_pk_fma_f32 v[4:5], v[54:55], v[4:5], v[6:7] op_sel_hi:[0,1,1]
	v_pk_fma_f32 v[2:3], v[54:55], v[2:3], v[8:9] op_sel_hi:[0,1,1]
	v_lshl_add_u32 v10, v10, 12, s4
	v_cvt_pk_bf16_f32 v4, v4, v5
	v_cvt_pk_bf16_f32 v5, v2, v3
	v_lshl_add_u64 v[2:3], v[10:11], 1, v[92:93]
	global_store_dwordx2 v[2:3], v[4:5], off
	v_mov_b32_e32 v2, v179
	s_mov_b64 s[72:73], -1
	v_and_b32_e32 v10, 15, v2
	v_or_b32_e32 v183, s19, v10
	v_lshl_add_u32 v3, v183, 2, s65
	ds_read2st64_b32 v[116:117], v3 offset1:2
	v_mad_u64_u32 v[52:53], s[2:3], v2, s71, v[114:115]
	ds_read2_b64 v[2:5], v52 offset1:4
	ds_read_b128 v[76:79], v178 offset:1024
	ds_read2_b64 v[6:9], v52 offset0:8 offset1:12
	ds_read2_b64 v[184:187], v52 offset0:16 offset1:20
	ds_read2_b64 v[80:83], v52 offset0:24 offset1:28
	s_waitcnt lgkmcnt(0)
	v_mfma_f32_16x16x32_bf16 v[2:5], v[24:27], v[2:5], 0
	v_mfma_f32_16x16x32_bf16 v[84:87], v[20:23], v[6:9], v[2:5]
	v_mfma_f32_16x16x32_bf16 v[2:5], v[16:19], v[184:187], v[84:87]
	s_andn2_b64 vcc, exec, s[16:17]
	s_cbranch_vccnz .LBB0_1886
	v_mfma_f32_16x16x32_bf16 v[2:5], v[12:15], v[80:83], v[2:5]

.LBB0_1888:
	s_nop 0
	s_nop 0
	s_nop 0
	s_nop 0
	s_nop 0
	s_nop 0
	s_nop 0
	s_nop 0
	s_nop 0
	s_nop 0
	s_nop 0
	s_nop 0
	s_nop 0
	s_nop 0
	s_nop 0
	s_nop 0
	s_nop 0
	s_nop 0
	s_nop 0
	s_nop 0
	s_nop 0
	s_nop 0
	v_readlane_b32 s0, v251, 47
	v_readlane_b32 s1, v251, 48
	s_and_b64 vcc, exec, s[0:1]
	s_cbranch_vccz .LBB0_1890
	v_readlane_b32 s0, v254, 0
	v_lshlrev_b32_e32 v4, 2, v115
	v_mov_b32_e32 v5, v11
	v_mov_b32_e32 v1, s0
	ds_read_b64 v[2:3], v1
	v_readlane_b32 s0, v251, 36
	s_add_i32 s0, s79, s0
	s_ashr_i32 s1, s0, 31
	s_lshl_b64 s[0:1], s[0:1], 21
	s_waitcnt lgkmcnt(0)
	v_readfirstlane_b32 s3, v2
	v_readfirstlane_b32 s2, v3
	s_add_u32 s0, s3, s0
	s_addc_u32 s1, s2, s1
	v_readlane_b32 s2, v253, 23
	s_add_u32 s0, s0, s2
	s_addc_u32 s1, s1, 0
	v_lshlrev_b32_e32 v2, 2, v126
	v_mov_b32_e32 v3, v11
	v_lshl_add_u64 v[2:3], s[0:1], 0, v[2:3]
	s_lshl_b32 s0, s45, 6
	s_ashr_i32 s1, s0, 31
	v_lshl_add_u64 v[2:3], s[0:1], 2, v[2:3]
	v_lshl_add_u64 v[2:3], v[2:3], 0, v[4:5]
	s_mov_b64 s[0:1], 0x4364000
	v_lshl_add_u64 v[4:5], v[2:3], 0, s[0:1]
	v_add_co_u32_e32 v2, vcc, 0x4364000, v2
	s_nop 1
	v_addc_co_u32_e32 v3, vcc, 0, v3, vcc
	global_store_dwordx4 v[2:3], v[28:31], off
	global_store_dwordx4 v[4:5], v[32:35], off offset:64
	global_store_dwordx4 v[4:5], v[36:39], off offset:128
	global_store_dwordx4 v[4:5], v[40:43], off offset:192
